# attention steady loops: -mhat folded into QK MFMA C operand, 33 v_sub per step removed
# speedup vs baseline: 1.0020x; 1.0020x over previous
.LBB0_317:
	ds_read_b128 v[14:17], v233
	ds_read_b128 v[34:37], v233 offset:512
	s_cmp_lg_u32 0, -1
	s_cselect_b32 s0, 0, 0
	s_add_i32 s0, s0, s70
	s_waitcnt lgkmcnt(1)
	v_mfma_f32_32x32x16_bf16 v[18:33], v[14:17], v[10:13], 0
	s_add_i32 s1, s0, 0x6000
	s_mov_b32 s4, 0
	s_mov_b32 s5, s4
	s_mov_b32 s6, s4
	s_mov_b32 s7, s4
	s_mov_b32 s8, s4
	s_mov_b32 s9, s4
	s_waitcnt lgkmcnt(0)
	v_mfma_f32_32x32x16_bf16 v[34:49], v[34:37], v[10:13], 0
	ds_read_b128 v[10:13], v233 offset:2048
	ds_read_b128 v[14:17], v233 offset:2560
	s_mov_b32 s10, s4
	s_mov_b32 s11, s4
	s_mov_b32 s12, s4
	s_mov_b32 s13, s4
	s_mov_b32 s14, s4
	s_mov_b32 s15, s4
	s_waitcnt lgkmcnt(1)
	v_mfma_f32_32x32x16_bf16 v[18:33], v[10:13], v[6:9], v[18:33]
	s_mov_b32 s16, s4
	s_mov_b32 s17, s4
	s_mov_b32 s18, s4
	s_mov_b32 s19, s4
	v_mov_b32_e32 v214, 0
	s_waitcnt lgkmcnt(0)
	v_mfma_f32_32x32x16_bf16 v[34:49], v[14:17], v[6:9], v[34:49]
	ds_read_b128 v[6:9], v233 offset:4096
	ds_read_b128 v[10:13], v233 offset:4608
	s_waitcnt lgkmcnt(1)
	v_mfma_f32_32x32x16_bf16 v[18:33], v[6:9], v[2:5], v[18:33]
	ds_read_b128 v[6:9], v233 offset:6144
	ds_read_b128 v[54:57], v233 offset:6656
	s_waitcnt vmcnt(0) lgkmcnt(0)
	s_barrier
	s_mov_b32 s2, m0
	s_mov_b32 m0, s1
	s_nop 3
	global_load_lds_dwordx4 v210, s[46:47]
	s_mov_b32 m0, s2
	s_add_u32 s46, s46, 0x10000
	s_addc_u32 s47, s47, 0
	s_add_i32 s1, s0, 0xc000
	s_mov_b32 s2, m0
	s_mov_b32 m0, s1
	s_nop 3
	global_load_lds_dwordx4 v211, s[44:45]
	s_mov_b32 m0, s2
	s_waitcnt lgkmcnt(2)
	v_mfma_f32_32x32x16_bf16 v[34:49], v[10:13], v[2:5], v[34:49]
	s_add_i32 s0, s0, 0xe000
	s_mov_b32 s1, m0
	s_mov_b32 m0, s0
	s_nop 3
	global_load_lds_dwordx4 v212, s[44:45]
	s_mov_b32 m0, s1
	ds_read_b128 v[190:193], v233 offset:8192
	ds_read_b128 v[182:185], v233 offset:8704
	ds_read_b128 v[186:189], v233 offset:10240
	ds_read_b128 v[178:181], v233 offset:10752
	ds_read_b128 v[194:197], v213
	s_add_u32 s44, s44, 0x10000
	s_addc_u32 s45, s45, 0
	s_waitcnt lgkmcnt(6)
	v_mfma_f32_32x32x16_bf16 v[18:33], v[6:9], v[50:53], v[18:33]
	v_mov_b64_e32 v[2:3], s[4:5]
	v_mov_b64_e32 v[16:17], s[18:19]
	v_mov_b64_e32 v[4:5], s[6:7]
	v_mov_b64_e32 v[6:7], s[8:9]
	v_mov_b64_e32 v[8:9], s[10:11]
	v_mov_b64_e32 v[10:11], s[12:13]
	v_mov_b64_e32 v[12:13], s[14:15]
	s_waitcnt lgkmcnt(5)
	v_mfma_f32_32x32x16_bf16 v[34:49], v[54:57], v[50:53], v[34:49]
	s_nop 2
	v_max_f32_e32 v0, v19, v19
	v_max_f32_e32 v58, v18, v18
	v_max_f32_e32 v0, v58, v0
	v_mov_b64_e32 v[14:15], s[16:17]
	s_mov_b32 s6, -1
	s_mov_b32 s5, 0x8000
	s_movk_i32 s12, 0x4000
	s_nop 1
	v_max3_f32 v50, v20, v21, v35
	v_max3_f32 v0, v0, v34, v36
	v_max3_f32 v0, v0, v37, v22
	v_max3_f32 v50, v50, v24, v25
	v_max3_f32 v0, v0, v23, v38
	v_max3_f32 v50, v50, v40, v41
	v_max3_f32 v0, v0, v39, v26
	v_max3_f32 v50, v50, v28, v29
	v_max3_f32 v0, v0, v27, v42
	v_max3_f32 v50, v50, v44, v45
	v_max3_f32 v0, v0, v43, v30
	v_max3_f32 v50, v50, v32, v33
	v_max3_f32 v0, v0, v31, v46
	v_max3_f32 v50, v50, v48, v49
	v_max3_f32 v0, v0, v47, v50
	v_mov_b32_e32 v50, v0
	s_nop 1
	v_permlane32_swap_b32_e32 v0, v50
	v_max_f32_e32 v50, v50, v50
	v_max_f32_e32 v0, v0, v0
	v_max_f32_e32 v0, v0, v50
	v_sub_f32_e32 v18, v18, v0
	v_exp_f32_e32 v82, v18
	v_sub_f32_e32 v18, v34, v0
	v_exp_f32_e32 v66, v18
	v_sub_f32_e32 v18, v19, v0
	v_exp_f32_e32 v83, v18
	v_sub_f32_e32 v18, v35, v0
	v_exp_f32_e32 v67, v18
	v_sub_f32_e32 v18, v20, v0
	v_exp_f32_e32 v84, v18
	v_sub_f32_e32 v18, v36, v0
	v_exp_f32_e32 v68, v18
	v_sub_f32_e32 v18, v21, v0
	v_exp_f32_e32 v85, v18
	v_sub_f32_e32 v18, v37, v0
	v_exp_f32_e32 v69, v18
	v_sub_f32_e32 v18, v22, v0
	v_exp_f32_e32 v86, v18
	v_sub_f32_e32 v18, v38, v0
	v_exp_f32_e32 v70, v18
	v_sub_f32_e32 v18, v23, v0
	v_exp_f32_e32 v87, v18
	v_sub_f32_e32 v18, v39, v0
	v_exp_f32_e32 v71, v18
	v_sub_f32_e32 v18, v24, v0
	v_exp_f32_e32 v88, v18
	v_sub_f32_e32 v18, v40, v0
	v_exp_f32_e32 v72, v18
	v_sub_f32_e32 v18, v25, v0
	v_exp_f32_e32 v89, v18
	v_sub_f32_e32 v18, v41, v0
	v_exp_f32_e32 v73, v18
	v_sub_f32_e32 v18, v26, v0
	v_exp_f32_e32 v90, v18
	v_sub_f32_e32 v18, v42, v0
	v_exp_f32_e32 v74, v18
	v_sub_f32_e32 v18, v27, v0
	v_exp_f32_e32 v91, v18
	v_sub_f32_e32 v18, v43, v0
	v_exp_f32_e32 v75, v18
	v_sub_f32_e32 v18, v28, v0
	v_exp_f32_e32 v92, v18
	v_sub_f32_e32 v18, v44, v0
	v_exp_f32_e32 v76, v18
	v_sub_f32_e32 v18, v29, v0
	v_exp_f32_e32 v93, v18
	v_sub_f32_e32 v18, v45, v0
	v_exp_f32_e32 v77, v18
	v_sub_f32_e32 v18, v30, v0
	v_exp_f32_e32 v94, v18
	v_sub_f32_e32 v18, v46, v0
	v_exp_f32_e32 v78, v18
	v_sub_f32_e32 v18, v31, v0
	v_exp_f32_e32 v95, v18
	v_sub_f32_e32 v18, v47, v0
	v_exp_f32_e32 v79, v18
	v_sub_f32_e32 v18, v32, v0
	v_exp_f32_e32 v96, v18
	v_sub_f32_e32 v18, v48, v0
	v_exp_f32_e32 v80, v18
	v_sub_f32_e32 v18, v33, v0
	v_exp_f32_e32 v97, v18
	v_sub_f32_e32 v18, v49, v0
	v_exp_f32_e32 v81, v18
	v_mov_b64_e32 v[64:65], v[16:17]
	v_mov_b64_e32 v[48:49], v[16:17]
	v_mov_b64_e32 v[32:33], v[16:17]
	s_movk_i32 s15, 0x2000
	s_mov_b32 s8, 5
	s_mov_b32 s10, s79
	v_mov_b64_e32 v[62:63], v[14:15]
	v_mov_b64_e32 v[60:61], v[12:13]
	v_mov_b64_e32 v[58:59], v[10:11]
	v_mov_b64_e32 v[56:57], v[8:9]
	v_mov_b64_e32 v[54:55], v[6:7]
	v_mov_b64_e32 v[52:53], v[4:5]
	v_mov_b64_e32 v[50:51], v[2:3]
	v_mov_b64_e32 v[46:47], v[14:15]
	v_mov_b64_e32 v[44:45], v[12:13]
	v_mov_b64_e32 v[42:43], v[10:11]
	v_mov_b64_e32 v[40:41], v[8:9]
	v_mov_b64_e32 v[38:39], v[6:7]
	v_mov_b64_e32 v[36:37], v[4:5]
	v_mov_b64_e32 v[34:35], v[2:3]
	v_mov_b64_e32 v[30:31], v[14:15]
	v_mov_b64_e32 v[28:29], v[12:13]
	v_mov_b64_e32 v[26:27], v[10:11]
	v_mov_b64_e32 v[24:25], v[8:9]
	v_mov_b64_e32 v[22:23], v[6:7]
	v_mov_b64_e32 v[20:21], v[4:5]
	v_mov_b64_e32 v[18:19], v[2:3]
	s_movk_i32 s7, 0x4000
	v_sub_f32_e32 v130, 0, v0
	v_sub_f32_e32 v131, 0, v0
	v_sub_f32_e32 v132, 0, v0
	v_sub_f32_e32 v133, 0, v0
	v_sub_f32_e32 v134, 0, v0
	v_sub_f32_e32 v135, 0, v0
	v_sub_f32_e32 v136, 0, v0
	v_sub_f32_e32 v137, 0, v0
	v_sub_f32_e32 v138, 0, v0
	v_sub_f32_e32 v139, 0, v0
	v_sub_f32_e32 v140, 0, v0
	v_sub_f32_e32 v141, 0, v0
	v_sub_f32_e32 v142, 0, v0
	v_sub_f32_e32 v143, 0, v0
	v_sub_f32_e32 v144, 0, v0
	v_sub_f32_e32 v145, 0, v0
.LBB0_318:
	v_add_u32_e32 v202, s4, v234
	v_add_u32_e32 v162, s15, v233
	ds_read_b64_tr_b16 v[200:201], v202 offset:33280
	ds_read_b128 v[204:207], v162 offset:4096
	ds_read_b64_tr_b16 v[198:199], v202 offset:32768
	ds_read_b128 v[216:219], v213 offset:1024
	s_waitcnt lgkmcnt(4)
	v_mfma_f32_32x32x16_bf16 v[114:129], v[190:193], v[194:197], v[130:145]
	v_add_f32_e32 v98, v82, v83
	v_add_f32_e32 v98, v84, v98
	v_add_f32_e32 v98, v85, v98
	v_add_f32_e32 v98, v86, v98
	v_add_f32_e32 v98, v87, v98
	v_cvt_pk_bf16_f32 v174, v82, v83
	v_cvt_pk_bf16_f32 v175, v84, v85
	ds_read_b64_tr_b16 v[190:191], v202 offset:36864
	ds_read_b64_tr_b16 v[192:193], v202 offset:37376
	ds_read_b128 v[236:239], v162 offset:4608
	v_add_f32_e32 v82, v88, v98
	v_mfma_f32_32x32x16_bf16 v[98:113], v[182:185], v[194:197], v[130:145]
	v_add_f32_e32 v82, v89, v82
	v_add_f32_e32 v82, v90, v82
	v_add_f32_e32 v163, v91, v82
	v_cvt_pk_bf16_f32 v176, v86, v87
	v_cvt_pk_bf16_f32 v177, v88, v89
	ds_read_b64_tr_b16 v[84:85], v202 offset:34304
	ds_read_b128 v[182:185], v162 offset:6144
	ds_read_b64_tr_b16 v[82:83], v202 offset:33792
	ds_read_b128 v[194:197], v213 offset:2048
	s_waitcnt lgkmcnt(7)
	v_mfma_f32_32x32x16_bf16 v[114:129], v[186:189], v[216:219], v[114:129]
	v_add_f32_e32 v86, v92, v163
	v_add_f32_e32 v86, v93, v86
	v_add_f32_e32 v86, v94, v86
	v_add_f32_e32 v163, v95, v86
	v_cvt_pk_bf16_f32 v170, v90, v91
	v_cvt_pk_bf16_f32 v171, v92, v93
	ds_read_b64_tr_b16 v[86:87], v202 offset:37888
	ds_read_b64_tr_b16 v[88:89], v202 offset:38400
	ds_read_b128 v[186:189], v162 offset:6656
	v_mfma_f32_32x32x16_bf16 v[98:113], v[178:181], v[216:219], v[98:113]
	v_add_f32_e32 v90, v96, v163
	v_add_f32_e32 v90, v97, v90
	v_add_f32_e32 v90, v66, v90
	v_add_f32_e32 v162, v67, v90
	v_cvt_pk_bf16_f32 v172, v94, v95
	v_cvt_pk_bf16_f32 v173, v96, v97
	ds_read_b64_tr_b16 v[92:93], v202 offset:35328
	ds_read_b64_tr_b16 v[90:91], v202 offset:34816
	ds_read_b128 v[178:181], v213 offset:3072
	s_waitcnt lgkmcnt(6)
	v_mfma_f32_32x32x16_bf16 v[114:129], v[204:207], v[194:197], v[114:129]
	v_add_f32_e32 v94, v68, v162
	v_add_f32_e32 v94, v69, v94
	v_add_f32_e32 v94, v70, v94
	v_add_f32_e32 v162, v71, v94
	v_cvt_pk_bf16_f32 v166, v66, v67
	v_cvt_pk_bf16_f32 v167, v68, v69
	ds_read_b64_tr_b16 v[94:95], v202 offset:38912
	ds_read_b64_tr_b16 v[96:97], v202 offset:39424
	v_mfma_f32_32x32x16_bf16 v[98:113], v[236:239], v[194:197], v[98:113]
	v_add_f32_e32 v66, v72, v162
	v_add_f32_e32 v66, v73, v66
	v_add_f32_e32 v66, v74, v66
	v_add_f32_e32 v66, v75, v66
	v_cvt_pk_bf16_f32 v168, v70, v71
	v_cvt_pk_bf16_f32 v169, v72, v73
	ds_read_b64_tr_b16 v[70:71], v202 offset:35840
	ds_read_b64_tr_b16 v[72:73], v202 offset:36352
	s_waitcnt lgkmcnt(4)
	v_mfma_f32_32x32x16_bf16 v[114:129], v[182:185], v[178:181], v[114:129]
	v_add_f32_e32 v66, v76, v66
	v_add_f32_e32 v66, v77, v66
	v_add_f32_e32 v66, v78, v66
	v_add_f32_e32 v182, v79, v66
	v_cvt_pk_bf16_f32 v162, v74, v75
	v_cvt_pk_bf16_f32 v163, v76, v77
	ds_read_b64_tr_b16 v[66:67], v202 offset:39936
	ds_read_b64_tr_b16 v[68:69], v202 offset:40448
	v_mfma_f32_32x32x16_bf16 v[98:113], v[186:189], v[178:181], v[98:113]
	v_add_f32_e32 v74, v80, v182
	v_add_f32_e32 v74, v81, v74
	v_add_f32_e32 v74, 0, v74
	v_cvt_pk_bf16_f32 v164, v78, v79
	v_cvt_pk_bf16_f32 v165, v80, v81
	s_nop 0
	v_add_f32_e32 v194, v214, v74
	v_max_f32_e32 v74, v115, v115
	v_max_f32_e32 v75, v114, v114
	v_max_f32_e32 v74, v75, v74
	s_nop 1
	v_max3_f32 v75, v116, v117, v99
	v_max3_f32 v74, v74, v98, v100
	v_max3_f32 v74, v74, v101, v118
	v_max3_f32 v75, v75, v120, v121
	v_max3_f32 v74, v74, v119, v102
	v_max3_f32 v75, v75, v104, v105
	v_max3_f32 v74, v74, v103, v122
	v_max3_f32 v75, v75, v124, v125
	v_max3_f32 v74, v74, v123, v106
	v_max3_f32 v75, v75, v108, v109
	v_max3_f32 v74, v74, v107, v126
	v_max3_f32 v75, v75, v128, v129
	v_max3_f32 v74, v74, v127, v110
	v_max3_f32 v75, v75, v112, v113
	v_max3_f32 v74, v74, v111, v75
	s_add_i32 s0, s15, 0xffffe000
	v_mov_b32_e32 v75, v74
	s_cmp_lg_u32 s15, 0
	s_nop 0
	v_permlane32_swap_b32_e32 v74, v75
	s_cselect_b32 s0, s0, 0x6000
	v_max_f32_e32 v75, v75, v75
	v_max_f32_e32 v74, v74, v74
	s_add_i32 s0, s0, s71
	s_mov_b32 s1, m0
	s_mov_b32 m0, s0
	s_nop 3
	global_load_lds_dwordx4 v210, s[46:47]
	s_mov_b32 m0, s1
	v_max_f32_e32 v74, v74, v75
	s_add_i32 s0, s5, s72
	s_mov_b32 s1, m0
	s_mov_b32 m0, s0
	s_nop 3
	global_load_lds_dwordx4 v211, s[44:45]
	s_mov_b32 m0, s1
	s_addk_i32 s0, 0x2000
	s_mov_b32 s1, m0
	s_mov_b32 m0, s0
	s_nop 3
	global_load_lds_dwordx4 v212, s[44:45]
	s_mov_b32 m0, s1
	v_cmp_lt_f32_e32 vcc, s87, v74
	s_cmp_lg_u64 vcc, 0
	s_cselect_b64 s[0:1], -1, 0
	s_cbranch_vccnz .LBB0_326
.LBB0_319:
	v_mfma_f32_32x32x16_bf16 v[2:17], v[174:177], v[198:201], v[2:17]
	v_exp_f32_e32 v114, v114
	v_exp_f32_e32 v115, v115
	ds_read_b64_tr_b16 v[74:75], v202 offset:40960
	ds_read_b64_tr_b16 v[76:77], v202 offset:41472
	v_mfma_f32_32x32x16_bf16 v[50:65], v[174:177], v[190:193], v[50:65]
	v_exp_f32_e32 v116, v116
	v_exp_f32_e32 v117, v117
	ds_read_b64_tr_b16 v[78:79], v202 offset:45056
	ds_read_b64_tr_b16 v[80:81], v202 offset:45568
	v_mfma_f32_32x32x16_bf16 v[2:17], v[170:173], v[82:85], v[2:17]
	v_exp_f32_e32 v118, v118
	v_exp_f32_e32 v119, v119
	ds_read_b64_tr_b16 v[82:83], v202 offset:41984
	ds_read_b64_tr_b16 v[84:85], v202 offset:42496
	v_mfma_f32_32x32x16_bf16 v[50:65], v[170:173], v[86:89], v[50:65]
	v_exp_f32_e32 v120, v120
	v_exp_f32_e32 v121, v121
	ds_read_b64_tr_b16 v[86:87], v202 offset:46080
	ds_read_b64_tr_b16 v[88:89], v202 offset:46592
	v_mfma_f32_32x32x16_bf16 v[2:17], v[166:169], v[90:93], v[2:17]
	v_exp_f32_e32 v122, v122
	v_exp_f32_e32 v123, v123
	ds_read_b64_tr_b16 v[90:91], v202 offset:43008
	ds_read_b64_tr_b16 v[92:93], v202 offset:43520
	s_waitcnt lgkmcnt(14)
	v_mfma_f32_32x32x16_bf16 v[50:65], v[166:169], v[94:97], v[50:65]
	v_exp_f32_e32 v124, v124
	v_exp_f32_e32 v125, v125
	ds_read_b64_tr_b16 v[94:95], v202 offset:47104
	ds_read_b64_tr_b16 v[96:97], v202 offset:47616
	s_waitcnt lgkmcnt(14)
	v_mfma_f32_32x32x16_bf16 v[2:17], v[162:165], v[70:73], v[2:17]
	v_exp_f32_e32 v126, v126
	v_exp_f32_e32 v127, v127
	ds_read_b64_tr_b16 v[178:179], v202 offset:44032
	ds_read_b64_tr_b16 v[180:181], v202 offset:44544
	s_waitcnt lgkmcnt(14)
	v_mfma_f32_32x32x16_bf16 v[50:65], v[162:165], v[66:69], v[50:65]
	v_exp_f32_e32 v128, v128
	v_exp_f32_e32 v129, v129
	ds_read_b64_tr_b16 v[186:187], v202 offset:48128
	ds_read_b64_tr_b16 v[188:189], v202 offset:48640
	s_waitcnt lgkmcnt(14)
	v_mfma_f32_32x32x16_bf16 v[34:49], v[174:177], v[74:77], v[34:49]
	v_exp_f32_e32 v98, v98
	v_exp_f32_e32 v99, v99
	s_waitcnt lgkmcnt(12)
	v_mfma_f32_32x32x16_bf16 v[18:33], v[174:177], v[78:81], v[18:33]
	v_exp_f32_e32 v100, v100
	v_exp_f32_e32 v101, v101
	s_waitcnt lgkmcnt(10)
	v_mfma_f32_32x32x16_bf16 v[34:49], v[170:173], v[82:85], v[34:49]
	v_exp_f32_e32 v102, v102
	v_exp_f32_e32 v103, v103
	s_waitcnt lgkmcnt(8)
	v_mfma_f32_32x32x16_bf16 v[18:33], v[170:173], v[86:89], v[18:33]
	v_exp_f32_e32 v104, v104
	v_exp_f32_e32 v105, v105
	v_add_u32_e32 v196, s12, v233
	ds_read_b128 v[66:69], v196
	s_waitcnt lgkmcnt(7)
	v_mfma_f32_32x32x16_bf16 v[34:49], v[166:169], v[90:93], v[34:49]
	v_exp_f32_e32 v106, v106
	v_exp_f32_e32 v107, v107
	ds_read_b128 v[70:73], v196 offset:512
	s_waitcnt lgkmcnt(6)
	v_mfma_f32_32x32x16_bf16 v[18:33], v[166:169], v[94:97], v[18:33]
	v_exp_f32_e32 v108, v108
	v_exp_f32_e32 v109, v109
	ds_read_b128 v[182:185], v196 offset:2048
	s_waitcnt lgkmcnt(5)
	v_mfma_f32_32x32x16_bf16 v[34:49], v[162:165], v[178:181], v[34:49]
	v_exp_f32_e32 v110, v110
	v_exp_f32_e32 v111, v111
	ds_read_b128 v[178:181], v196 offset:2560
	ds_read_b128 v[74:77], v213
	s_waitcnt lgkmcnt(5)
	v_mfma_f32_32x32x16_bf16 v[18:33], v[162:165], v[186:189], v[18:33]
	v_exp_f32_e32 v112, v112
	v_exp_f32_e32 v113, v113
	s_waitcnt vmcnt(3) lgkmcnt(0)
	s_barrier
	s_andn2_b64 vcc, exec, s[0:1]
	s_cbranch_vccnz .LBB0_321
	s_waitcnt lgkmcnt(0)
	s_mov_b32 s0, 0
	s_nop 0
	v_mbcnt_lo_u32_b32 v78, -1, s0
	v_mbcnt_hi_u32_b32 v78, -1, v78
	v_ashrrev_i32_e32 v78, 3, v78
	v_lshlrev_b32_e32 v78, 2, v78
	v_and_b32_e32 v78, -16, v78
	v_add_u32_e32 v90, s76, v78
	ds_read_b128 v[78:81], v90 offset:96
	ds_read_b128 v[82:85], v90 offset:64
	ds_read_b128 v[86:89], v90 offset:32
	ds_read_b128 v[90:93], v90
	s_waitcnt lgkmcnt(3)
	v_pk_mul_f32 v[14:15], v[14:15], v[78:79]
	s_waitcnt lgkmcnt(2)
	v_pk_mul_f32 v[10:11], v[10:11], v[82:83]
	s_waitcnt lgkmcnt(1)
	v_pk_mul_f32 v[6:7], v[6:7], v[86:87]
	v_pk_mul_f32 v[16:17], v[16:17], v[80:81]
	v_pk_mul_f32 v[12:13], v[12:13], v[84:85]
	v_pk_mul_f32 v[8:9], v[8:9], v[88:89]
	s_waitcnt lgkmcnt(0)
	v_pk_mul_f32 v[4:5], v[4:5], v[92:93]
	v_pk_mul_f32 v[2:3], v[2:3], v[90:91]
	v_pk_mul_f32 v[62:63], v[62:63], v[78:79]
	v_pk_mul_f32 v[58:59], v[58:59], v[82:83]
	v_pk_mul_f32 v[54:55], v[54:55], v[86:87]
	v_pk_mul_f32 v[64:65], v[64:65], v[80:81]
	v_pk_mul_f32 v[60:61], v[60:61], v[84:85]
	v_pk_mul_f32 v[56:57], v[56:57], v[88:89]
	v_pk_mul_f32 v[52:53], v[52:53], v[92:93]
	v_pk_mul_f32 v[50:51], v[50:51], v[90:91]
	v_pk_mul_f32 v[46:47], v[46:47], v[78:79]
	v_pk_mul_f32 v[42:43], v[42:43], v[82:83]
	v_pk_mul_f32 v[38:39], v[38:39], v[86:87]
	v_pk_mul_f32 v[48:49], v[48:49], v[80:81]
	v_pk_mul_f32 v[44:45], v[44:45], v[84:85]
	v_pk_mul_f32 v[40:41], v[40:41], v[88:89]
	v_pk_mul_f32 v[36:37], v[36:37], v[92:93]
	v_pk_mul_f32 v[34:35], v[34:35], v[90:91]
	v_pk_mul_f32 v[30:31], v[30:31], v[78:79]
	v_pk_mul_f32 v[26:27], v[26:27], v[82:83]
	v_pk_mul_f32 v[22:23], v[22:23], v[86:87]
	v_pk_mul_f32 v[32:33], v[32:33], v[80:81]
	v_pk_mul_f32 v[28:29], v[28:29], v[84:85]
	v_pk_mul_f32 v[24:25], v[24:25], v[88:89]
	v_pk_mul_f32 v[20:21], v[20:21], v[92:93]
	v_pk_mul_f32 v[18:19], v[18:19], v[90:91]
.LBB0_321:
	s_add_u32 s2, s46, 0x10000
	s_addc_u32 s3, s47, 0
	s_add_u32 s0, s44, 0x10000
	s_addc_u32 s1, s45, 0
	s_add_i32 s4, s5, 0x4000
	s_cmpk_lg_u32 s5, 0x8000
	s_cselect_b32 s11, s4, 0
	v_add_u32_e32 v195, s7, v234
	ds_read_b64_tr_b16 v[190:191], v195 offset:32768
	ds_read_b64_tr_b16 v[192:193], v195 offset:33280
	ds_read_b128 v[198:201], v196 offset:4096
	ds_read_b128 v[202:205], v213 offset:1024
	s_waitcnt lgkmcnt(4)
	v_mfma_f32_32x32x16_bf16 v[82:97], v[66:69], v[74:77], v[130:145]
	v_add_f32_e32 v78, v114, v115
	v_add_f32_e32 v78, v116, v78
	v_add_f32_e32 v78, v117, v78
	v_add_f32_e32 v78, v118, v78
	v_add_f32_e32 v78, v119, v78
	v_cvt_pk_bf16_f32 v174, v114, v115
	v_cvt_pk_bf16_f32 v175, v116, v117
	ds_read_b64_tr_b16 v[188:189], v195 offset:37376
	ds_read_b64_tr_b16 v[186:187], v195 offset:36864
	ds_read_b128 v[206:209], v196 offset:4608
	v_add_f32_e32 v66, v120, v78
	v_add_f32_e32 v66, v121, v66
	v_add_f32_e32 v66, v122, v66
	v_add_f32_e32 v162, v123, v66
	v_mfma_f32_32x32x16_bf16 v[66:81], v[70:73], v[74:77], v[130:145]
	v_cvt_pk_bf16_f32 v176, v118, v119
	v_cvt_pk_bf16_f32 v177, v120, v121
	ds_read_b64_tr_b16 v[114:115], v195 offset:33792
	ds_read_b64_tr_b16 v[116:117], v195 offset:34304
	ds_read_b128 v[214:217], v196 offset:6144
	ds_read_b128 v[236:239], v213 offset:2048
	s_waitcnt lgkmcnt(7)
	v_mfma_f32_32x32x16_bf16 v[82:97], v[182:185], v[202:205], v[82:97]
	v_add_f32_e32 v118, v124, v162
	v_add_f32_e32 v118, v125, v118
	v_add_f32_e32 v118, v126, v118
	v_add_f32_e32 v162, v127, v118
	v_cvt_pk_bf16_f32 v170, v122, v123
	v_cvt_pk_bf16_f32 v171, v124, v125
	ds_read_b64_tr_b16 v[120:121], v195 offset:38400
	ds_read_b64_tr_b16 v[118:119], v195 offset:37888
	ds_read_b128 v[182:185], v196 offset:6656
	v_mfma_f32_32x32x16_bf16 v[66:81], v[178:181], v[202:205], v[66:81]
	v_add_f32_e32 v122, v128, v162
	v_add_f32_e32 v122, v129, v122
	v_add_f32_e32 v122, v98, v122
	v_add_f32_e32 v162, v99, v122
	v_cvt_pk_bf16_f32 v172, v126, v127
	v_cvt_pk_bf16_f32 v173, v128, v129
	ds_read_b64_tr_b16 v[124:125], v195 offset:35328
	ds_read_b64_tr_b16 v[122:123], v195 offset:34816
	ds_read_b128 v[178:181], v213 offset:3072
	s_waitcnt lgkmcnt(6)
	v_mfma_f32_32x32x16_bf16 v[82:97], v[198:201], v[236:239], v[82:97]
	v_add_f32_e32 v126, v100, v162
	v_add_f32_e32 v126, v101, v126
	v_add_f32_e32 v126, v102, v126
	v_add_f32_e32 v162, v103, v126
	v_cvt_pk_bf16_f32 v166, v98, v99
	v_cvt_pk_bf16_f32 v167, v100, v101
	ds_read_b64_tr_b16 v[126:127], v195 offset:38912
	ds_read_b64_tr_b16 v[128:129], v195 offset:39424
	v_mfma_f32_32x32x16_bf16 v[66:81], v[206:209], v[236:239], v[66:81]
	v_add_f32_e32 v98, v104, v162
	v_add_f32_e32 v98, v105, v98
	v_add_f32_e32 v98, v106, v98
	v_add_f32_e32 v98, v107, v98
	v_cvt_pk_bf16_f32 v168, v102, v103
	v_cvt_pk_bf16_f32 v169, v104, v105
	ds_read_b64_tr_b16 v[102:103], v195 offset:35840
	ds_read_b64_tr_b16 v[104:105], v195 offset:36352
	s_waitcnt lgkmcnt(4)
	v_mfma_f32_32x32x16_bf16 v[82:97], v[214:217], v[178:181], v[82:97]
	v_add_f32_e32 v98, v108, v98
	v_add_f32_e32 v98, v109, v98
	v_add_f32_e32 v98, v110, v98
	v_add_f32_e32 v196, v111, v98
	v_cvt_pk_bf16_f32 v162, v106, v107
	v_cvt_pk_bf16_f32 v163, v108, v109
	ds_read_b64_tr_b16 v[98:99], v195 offset:39936
	ds_read_b64_tr_b16 v[100:101], v195 offset:40448
	v_mfma_f32_32x32x16_bf16 v[66:81], v[182:185], v[178:181], v[66:81]
	v_add_f32_e32 v106, v112, v196
	v_add_f32_e32 v106, v113, v106
	v_add_f32_e32 v106, 0, v106
	v_cvt_pk_bf16_f32 v164, v110, v111
	v_cvt_pk_bf16_f32 v165, v112, v113
	s_nop 0
	v_add_f32_e32 v214, v194, v106
	v_max_f32_e32 v106, v83, v83
	v_max_f32_e32 v107, v82, v82
	v_max_f32_e32 v106, v107, v106
	s_nop 1
	v_max3_f32 v107, v84, v85, v67
	v_max3_f32 v106, v106, v66, v68
	v_max3_f32 v106, v106, v69, v86
	v_max3_f32 v107, v107, v88, v89
	v_max3_f32 v106, v106, v87, v70
	v_max3_f32 v107, v107, v72, v73
	v_max3_f32 v106, v106, v71, v90
	v_max3_f32 v107, v107, v92, v93
	v_max3_f32 v106, v106, v91, v74
	v_max3_f32 v107, v107, v76, v77
	v_max3_f32 v106, v106, v75, v94
	v_max3_f32 v107, v107, v96, v97
	v_max3_f32 v106, v106, v95, v78
	v_max3_f32 v107, v107, v80, v81
	v_max3_f32 v106, v106, v79, v107
	s_add_i32 s4, s12, 0xffffe000
	v_mov_b32_e32 v107, v106
	s_cmp_lg_u32 s12, 0
	s_nop 0
	v_permlane32_swap_b32_e32 v106, v107
	s_cselect_b32 s4, s4, 0x6000
	v_max_f32_e32 v107, v107, v107
	v_max_f32_e32 v106, v106, v106
	s_add_i32 s4, s4, s71
	s_mov_b32 s7, m0
	s_mov_b32 m0, s4
	s_nop 3
	global_load_lds_dwordx4 v210, s[2:3]
	s_mov_b32 m0, s7
	v_max_f32_e32 v106, v106, v107
	s_add_i32 s2, s11, s72
	s_mov_b32 s3, m0
	s_mov_b32 m0, s2
	s_nop 3
	global_load_lds_dwordx4 v211, s[0:1]
	s_mov_b32 m0, s3
	s_addk_i32 s2, 0x2000
	s_mov_b32 s3, m0
	s_mov_b32 m0, s2
	s_nop 3
	global_load_lds_dwordx4 v212, s[0:1]
	s_mov_b32 m0, s3
	v_cmp_lt_f32_e32 vcc, s87, v106
	s_cmp_lg_u64 vcc, 0
	s_cselect_b64 s[0:1], -1, 0
	s_cbranch_vccnz .LBB0_329
.LBB0_322:
	s_add_i32 s2, s12, 0x2000
	s_cmpk_lg_i32 s12, 0x6000
	s_cselect_b32 s15, s2, 0
	v_mfma_f32_32x32x16_bf16 v[2:17], v[174:177], v[190:193], v[2:17]
	v_exp_f32_e32 v82, v82
	v_exp_f32_e32 v83, v83
	ds_read_b64_tr_b16 v[106:107], v195 offset:40960
	ds_read_b64_tr_b16 v[108:109], v195 offset:41472
	v_mfma_f32_32x32x16_bf16 v[50:65], v[174:177], v[186:189], v[50:65]
	v_exp_f32_e32 v84, v84
	v_exp_f32_e32 v85, v85
	ds_read_b64_tr_b16 v[110:111], v195 offset:45056
	ds_read_b64_tr_b16 v[112:113], v195 offset:45568
	v_mfma_f32_32x32x16_bf16 v[2:17], v[170:173], v[114:117], v[2:17]
	v_exp_f32_e32 v86, v86
	v_exp_f32_e32 v87, v87
	ds_read_b64_tr_b16 v[114:115], v195 offset:41984
	ds_read_b64_tr_b16 v[116:117], v195 offset:42496
	v_mfma_f32_32x32x16_bf16 v[50:65], v[170:173], v[118:121], v[50:65]
	v_exp_f32_e32 v88, v88
	v_exp_f32_e32 v89, v89
	ds_read_b64_tr_b16 v[118:119], v195 offset:46080
	ds_read_b64_tr_b16 v[120:121], v195 offset:46592
	v_mfma_f32_32x32x16_bf16 v[2:17], v[166:169], v[122:125], v[2:17]
	v_exp_f32_e32 v90, v90
	v_exp_f32_e32 v91, v91
	ds_read_b64_tr_b16 v[122:123], v195 offset:43008
	ds_read_b64_tr_b16 v[124:125], v195 offset:43520
	s_waitcnt lgkmcnt(14)
	v_mfma_f32_32x32x16_bf16 v[50:65], v[166:169], v[126:129], v[50:65]
	v_exp_f32_e32 v92, v92
	v_exp_f32_e32 v93, v93
	ds_read_b64_tr_b16 v[126:127], v195 offset:47104
	ds_read_b64_tr_b16 v[128:129], v195 offset:47616
	s_waitcnt lgkmcnt(14)
	v_mfma_f32_32x32x16_bf16 v[2:17], v[162:165], v[102:105], v[2:17]
	v_exp_f32_e32 v94, v94
	v_exp_f32_e32 v95, v95
	ds_read_b64_tr_b16 v[102:103], v195 offset:44032
	ds_read_b64_tr_b16 v[104:105], v195 offset:44544
	s_waitcnt lgkmcnt(14)
	v_mfma_f32_32x32x16_bf16 v[50:65], v[162:165], v[98:101], v[50:65]
	v_exp_f32_e32 v96, v96
	v_exp_f32_e32 v97, v97
	ds_read_b64_tr_b16 v[98:99], v195 offset:48128
	ds_read_b64_tr_b16 v[100:101], v195 offset:48640
	s_waitcnt lgkmcnt(14)
	v_mfma_f32_32x32x16_bf16 v[34:49], v[174:177], v[106:109], v[34:49]
	v_exp_f32_e32 v66, v66
	v_exp_f32_e32 v67, v67
	s_waitcnt lgkmcnt(12)
	v_mfma_f32_32x32x16_bf16 v[18:33], v[174:177], v[110:113], v[18:33]
	v_exp_f32_e32 v68, v68
	v_exp_f32_e32 v69, v69
	s_waitcnt lgkmcnt(10)
	v_mfma_f32_32x32x16_bf16 v[34:49], v[170:173], v[114:117], v[34:49]
	v_exp_f32_e32 v70, v70
	v_exp_f32_e32 v71, v71
	s_waitcnt lgkmcnt(8)
	v_mfma_f32_32x32x16_bf16 v[18:33], v[170:173], v[118:121], v[18:33]
	v_exp_f32_e32 v72, v72
	v_exp_f32_e32 v73, v73
	v_add_u32_e32 v106, s15, v233
	ds_read_b128 v[190:193], v106
	s_waitcnt lgkmcnt(7)
	v_mfma_f32_32x32x16_bf16 v[34:49], v[166:169], v[122:125], v[34:49]
	v_exp_f32_e32 v74, v74
	v_exp_f32_e32 v75, v75
	ds_read_b128 v[182:185], v106 offset:512
	s_waitcnt lgkmcnt(6)
	v_mfma_f32_32x32x16_bf16 v[18:33], v[166:169], v[126:129], v[18:33]
	v_exp_f32_e32 v76, v76
	v_exp_f32_e32 v77, v77
	ds_read_b128 v[186:189], v106 offset:2048
	s_waitcnt lgkmcnt(5)
	v_mfma_f32_32x32x16_bf16 v[34:49], v[162:165], v[102:105], v[34:49]
	v_exp_f32_e32 v78, v78
	v_exp_f32_e32 v79, v79
	ds_read_b128 v[178:181], v106 offset:2560
	ds_read_b128 v[194:197], v213
	s_waitcnt lgkmcnt(5)
	v_mfma_f32_32x32x16_bf16 v[18:33], v[162:165], v[98:101], v[18:33]
	v_exp_f32_e32 v80, v80
	v_exp_f32_e32 v81, v81
	s_waitcnt vmcnt(3) lgkmcnt(0)
	s_barrier
	s_andn2_b64 vcc, exec, s[0:1]
	s_cbranch_vccnz .LBB0_324
	s_waitcnt lgkmcnt(0)
	s_mov_b32 s0, 0
	s_nop 0
	v_mbcnt_lo_u32_b32 v98, -1, s0
	v_mbcnt_hi_u32_b32 v98, -1, v98
	v_ashrrev_i32_e32 v98, 3, v98
	v_lshlrev_b32_e32 v98, 2, v98
	v_and_b32_e32 v98, -16, v98
	v_add_u32_e32 v110, s76, v98
	ds_read_b128 v[98:101], v110 offset:96
	ds_read_b128 v[102:105], v110 offset:64
	ds_read_b128 v[106:109], v110 offset:32
	ds_read_b128 v[110:113], v110
	s_waitcnt lgkmcnt(3)
	v_pk_mul_f32 v[14:15], v[14:15], v[98:99]
	s_waitcnt lgkmcnt(2)
	v_pk_mul_f32 v[10:11], v[10:11], v[102:103]
	s_waitcnt lgkmcnt(1)
	v_pk_mul_f32 v[6:7], v[6:7], v[106:107]
	v_pk_mul_f32 v[16:17], v[16:17], v[100:101]
	v_pk_mul_f32 v[12:13], v[12:13], v[104:105]
	v_pk_mul_f32 v[8:9], v[8:9], v[108:109]
	s_waitcnt lgkmcnt(0)
	v_pk_mul_f32 v[4:5], v[4:5], v[112:113]
	v_pk_mul_f32 v[2:3], v[2:3], v[110:111]
	v_pk_mul_f32 v[62:63], v[62:63], v[98:99]
	v_pk_mul_f32 v[58:59], v[58:59], v[102:103]
	v_pk_mul_f32 v[54:55], v[54:55], v[106:107]
	v_pk_mul_f32 v[64:65], v[64:65], v[100:101]
	v_pk_mul_f32 v[60:61], v[60:61], v[104:105]
	v_pk_mul_f32 v[56:57], v[56:57], v[108:109]
	v_pk_mul_f32 v[52:53], v[52:53], v[112:113]
	v_pk_mul_f32 v[50:51], v[50:51], v[110:111]
	v_pk_mul_f32 v[46:47], v[46:47], v[98:99]
	v_pk_mul_f32 v[42:43], v[42:43], v[102:103]
	v_pk_mul_f32 v[38:39], v[38:39], v[106:107]
	v_pk_mul_f32 v[48:49], v[48:49], v[100:101]
	v_pk_mul_f32 v[44:45], v[44:45], v[104:105]
	v_pk_mul_f32 v[40:41], v[40:41], v[108:109]
	v_pk_mul_f32 v[36:37], v[36:37], v[112:113]
	v_pk_mul_f32 v[34:35], v[34:35], v[110:111]
	v_pk_mul_f32 v[30:31], v[30:31], v[98:99]
	v_pk_mul_f32 v[26:27], v[26:27], v[102:103]
	v_pk_mul_f32 v[22:23], v[22:23], v[106:107]
	v_pk_mul_f32 v[32:33], v[32:33], v[100:101]
	v_pk_mul_f32 v[28:29], v[28:29], v[104:105]
	v_pk_mul_f32 v[24:25], v[24:25], v[108:109]
	v_pk_mul_f32 v[20:21], v[20:21], v[112:113]
	v_pk_mul_f32 v[18:19], v[18:19], v[110:111]

.LBB0_326:
	v_max_f32_e32 v74, v74, v74
	v_max_f32_e32 v75, 0, v74
	v_exp_f32_e64 v74, -v75
	s_mov_b32 s2, 0
	s_nop 0
	v_mbcnt_lo_u32_b32 v76, -1, s2
	v_mbcnt_hi_u32_b32 v76, -1, v76
	v_cmp_gt_i32_e32 vcc, 32, v76
	s_and_saveexec_b64 s[2:3], vcc
	v_lshl_add_u32 v76, v76, 2, s76
	ds_write_b32 v76, v74
	s_or_b64 exec, exec, s[2:3]
	v_add_f32_e32 v0, v0, v75
	v_sub_f32_e32 v114, v114, v75
	v_sub_f32_e32 v115, v115, v75
	v_sub_f32_e32 v116, v116, v75
	v_sub_f32_e32 v117, v117, v75
	v_sub_f32_e32 v118, v118, v75
	v_sub_f32_e32 v119, v119, v75
	v_sub_f32_e32 v120, v120, v75
	v_sub_f32_e32 v121, v121, v75
	v_sub_f32_e32 v122, v122, v75
	v_sub_f32_e32 v123, v123, v75
	v_sub_f32_e32 v124, v124, v75
	v_sub_f32_e32 v125, v125, v75
	v_sub_f32_e32 v126, v126, v75
	v_sub_f32_e32 v127, v127, v75
	v_sub_f32_e32 v128, v128, v75
	v_sub_f32_e32 v129, v129, v75
	v_sub_f32_e32 v98, v98, v75
	v_sub_f32_e32 v99, v99, v75
	v_sub_f32_e32 v100, v100, v75
	v_sub_f32_e32 v101, v101, v75
	v_sub_f32_e32 v102, v102, v75
	v_sub_f32_e32 v103, v103, v75
	v_sub_f32_e32 v104, v104, v75
	v_sub_f32_e32 v105, v105, v75
	v_sub_f32_e32 v106, v106, v75
	v_sub_f32_e32 v107, v107, v75
	v_sub_f32_e32 v108, v108, v75
	v_sub_f32_e32 v109, v109, v75
	v_sub_f32_e32 v110, v110, v75
	v_sub_f32_e32 v111, v111, v75
	v_sub_f32_e32 v112, v112, v75
	v_sub_f32_e32 v113, v113, v75
	v_sub_f32_e32 v130, v130, v75
	v_sub_f32_e32 v131, v131, v75
	v_sub_f32_e32 v132, v132, v75
	v_sub_f32_e32 v133, v133, v75
	v_sub_f32_e32 v134, v134, v75
	v_sub_f32_e32 v135, v135, v75
	v_sub_f32_e32 v136, v136, v75
	v_sub_f32_e32 v137, v137, v75
	v_sub_f32_e32 v138, v138, v75
	v_sub_f32_e32 v139, v139, v75
	v_sub_f32_e32 v140, v140, v75
	v_sub_f32_e32 v141, v141, v75
	v_sub_f32_e32 v142, v142, v75
	v_sub_f32_e32 v143, v143, v75
	v_sub_f32_e32 v144, v144, v75
	v_sub_f32_e32 v145, v145, v75
	v_mul_f32_e32 v194, v194, v74
	s_branch .LBB0_319
.LBB0_329:
	v_max_f32_e32 v106, v106, v106
	v_max_f32_e32 v107, 0, v106
	v_exp_f32_e64 v106, -v107
	s_mov_b32 s2, 0
	s_nop 0
	v_mbcnt_lo_u32_b32 v108, -1, s2
	v_mbcnt_hi_u32_b32 v108, -1, v108
	v_cmp_gt_i32_e32 vcc, 32, v108
	s_and_saveexec_b64 s[2:3], vcc
	v_lshl_add_u32 v108, v108, 2, s76
	ds_write_b32 v108, v106
	s_or_b64 exec, exec, s[2:3]
	v_add_f32_e32 v0, v0, v107
	v_sub_f32_e32 v82, v82, v107
	v_sub_f32_e32 v83, v83, v107
	v_sub_f32_e32 v84, v84, v107
	v_sub_f32_e32 v85, v85, v107
	v_sub_f32_e32 v86, v86, v107
	v_sub_f32_e32 v87, v87, v107
	v_sub_f32_e32 v88, v88, v107
	v_sub_f32_e32 v89, v89, v107
	v_sub_f32_e32 v90, v90, v107
	v_sub_f32_e32 v91, v91, v107
	v_sub_f32_e32 v92, v92, v107
	v_sub_f32_e32 v93, v93, v107
	v_sub_f32_e32 v94, v94, v107
	v_sub_f32_e32 v95, v95, v107
	v_sub_f32_e32 v96, v96, v107
	v_sub_f32_e32 v97, v97, v107
	v_sub_f32_e32 v66, v66, v107
	v_sub_f32_e32 v67, v67, v107
	v_sub_f32_e32 v68, v68, v107
	v_sub_f32_e32 v69, v69, v107
	v_sub_f32_e32 v70, v70, v107
	v_sub_f32_e32 v71, v71, v107
	v_sub_f32_e32 v72, v72, v107
	v_sub_f32_e32 v73, v73, v107
	v_sub_f32_e32 v74, v74, v107
	v_sub_f32_e32 v75, v75, v107
	v_sub_f32_e32 v76, v76, v107
	v_sub_f32_e32 v77, v77, v107
	v_sub_f32_e32 v78, v78, v107
	v_sub_f32_e32 v79, v79, v107
	v_sub_f32_e32 v80, v80, v107
	v_sub_f32_e32 v81, v81, v107
	v_sub_f32_e32 v130, v130, v107
	v_sub_f32_e32 v131, v131, v107
	v_sub_f32_e32 v132, v132, v107
	v_sub_f32_e32 v133, v133, v107
	v_sub_f32_e32 v134, v134, v107
	v_sub_f32_e32 v135, v135, v107
	v_sub_f32_e32 v136, v136, v107
	v_sub_f32_e32 v137, v137, v107
	v_sub_f32_e32 v138, v138, v107
	v_sub_f32_e32 v139, v139, v107
	v_sub_f32_e32 v140, v140, v107
	v_sub_f32_e32 v141, v141, v107
	v_sub_f32_e32 v142, v142, v107
	v_sub_f32_e32 v143, v143, v107
	v_sub_f32_e32 v144, v144, v107
	v_sub_f32_e32 v145, v145, v107
	v_mul_f32_e32 v214, v214, v106
	s_branch .LBB0_322

.LBB0_409:
	s_nop 8
	v_max_f32_e32 v0, v19, v19
	v_max_f32_e32 v34, v18, v18
	v_max_f32_e32 v0, v34, v0
	v_max3_f32 v34, v20, v21, v3
	v_max3_f32 v0, v0, v2, v4
	v_max3_f32 v0, v0, v5, v22
	v_max3_f32 v34, v34, v24, v25
	v_max3_f32 v0, v0, v23, v6
	v_max3_f32 v34, v34, v8, v9
	v_max3_f32 v0, v0, v7, v26
	v_max3_f32 v34, v34, v28, v29
	v_max3_f32 v0, v0, v27, v10
	v_max3_f32 v34, v34, v12, v13
	v_max3_f32 v0, v0, v11, v30
	v_max3_f32 v34, v34, v32, v33
	v_max3_f32 v0, v0, v31, v14
	v_max3_f32 v34, v34, v16, v17
	v_max3_f32 v0, v0, v15, v34
	v_mov_b32_e32 v34, v0
	s_nop 1
	v_permlane32_swap_b32_e32 v0, v34
	v_max_f32_e32 v34, v34, v34
	v_max_f32_e32 v0, v0, v0
	v_max_f32_e32 v239, v0, v34
	v_sub_f32_e32 v0, v18, v239
	v_exp_f32_e32 v96, v0
	v_sub_f32_e32 v0, v2, v239
	v_exp_f32_e32 v80, v0
	v_sub_f32_e32 v0, v19, v239
	v_exp_f32_e32 v97, v0
	v_sub_f32_e32 v0, v3, v239
	v_exp_f32_e32 v81, v0
	v_sub_f32_e32 v0, v20, v239
	v_exp_f32_e32 v98, v0
	v_sub_f32_e32 v0, v4, v239
	v_exp_f32_e32 v82, v0
	v_sub_f32_e32 v0, v21, v239
	v_exp_f32_e32 v99, v0
	v_sub_f32_e32 v0, v5, v239
	v_exp_f32_e32 v83, v0
	v_sub_f32_e32 v0, v22, v239
	v_exp_f32_e32 v100, v0
	v_sub_f32_e32 v0, v6, v239
	v_exp_f32_e32 v84, v0
	v_sub_f32_e32 v0, v23, v239
	v_exp_f32_e32 v101, v0
	v_sub_f32_e32 v0, v7, v239
	v_exp_f32_e32 v85, v0
	v_sub_f32_e32 v0, v24, v239
	v_exp_f32_e32 v102, v0
	v_sub_f32_e32 v0, v8, v239
	v_exp_f32_e32 v86, v0
	v_sub_f32_e32 v0, v25, v239
	v_exp_f32_e32 v103, v0
	v_sub_f32_e32 v0, v9, v239
	v_exp_f32_e32 v87, v0
	v_sub_f32_e32 v0, v26, v239
	v_exp_f32_e32 v104, v0
	v_sub_f32_e32 v0, v10, v239
	v_exp_f32_e32 v88, v0
	v_sub_f32_e32 v0, v27, v239
	v_exp_f32_e32 v105, v0
	v_sub_f32_e32 v0, v11, v239
	v_exp_f32_e32 v89, v0
	v_sub_f32_e32 v0, v28, v239
	v_exp_f32_e32 v106, v0
	v_sub_f32_e32 v0, v12, v239
	s_cmp_lg_u32 0, -1
	v_exp_f32_e32 v90, v0
	v_sub_f32_e32 v0, v29, v239
	s_cselect_b32 s0, 0, 0
	v_exp_f32_e32 v107, v0
	v_sub_f32_e32 v0, v13, v239
	s_add_i32 s0, s0, s45
	v_exp_f32_e32 v91, v0
	v_sub_f32_e32 v0, v30, v239
	s_waitcnt vmcnt(0) lgkmcnt(0)
	s_barrier
	s_add_i32 s1, s0, 0x6000
	v_exp_f32_e32 v108, v0
	v_sub_f32_e32 v0, v14, v239
	s_mov_b32 s2, m0
	s_mov_b32 m0, s1
	s_nop 3
	global_load_lds_dwordx4 v236, s[24:25]
	s_mov_b32 m0, s2
	s_add_u32 s24, s24, 0x10000
	v_exp_f32_e32 v92, v0
	v_sub_f32_e32 v0, v31, v239
	s_addc_u32 s25, s25, 0
	s_add_i32 s1, s0, 0xc000
	s_mov_b32 s2, m0
	s_mov_b32 m0, s1
	s_nop 3
	global_load_lds_dwordx4 v237, s[14:15]
	s_mov_b32 m0, s2
	v_exp_f32_e32 v109, v0
	v_sub_f32_e32 v0, v15, v239
	s_add_i32 s0, s0, 0xe000
	s_mov_b32 s1, m0
	s_mov_b32 m0, s0
	s_nop 3
	global_load_lds_dwordx4 v238, s[14:15]
	s_mov_b32 m0, s1
	v_exp_f32_e32 v93, v0
	v_sub_f32_e32 v0, v32, v239
	ds_read_b128 v[204:207], v233 offset:8192
	ds_read_b128 v[196:199], v233 offset:8704
	ds_read_b128 v[200:203], v233 offset:10240
	ds_read_b128 v[192:195], v233 offset:10752
	ds_read_b128 v[208:211], v240
	v_exp_f32_e32 v110, v0
	v_sub_f32_e32 v0, v16, v239
	v_exp_f32_e32 v94, v0
	v_sub_f32_e32 v0, v33, v239
	v_exp_f32_e32 v111, v0
	v_sub_f32_e32 v0, v17, v239
	v_exp_f32_e32 v95, v0
	s_add_u32 s14, s14, 0x10000
	s_mov_b32 s4, 0
	s_addc_u32 s15, s15, 0
	s_andn2_b64 vcc, exec, s[8:9]
	s_mov_b32 s72, 1
	s_cbranch_vccnz .LBB0_425
	v_mov_b32_e32 v14, v1
	v_mov_b32_e32 v15, v1
	v_mov_b32_e32 v0, v1
	v_mov_b32_e32 v2, v1
	v_mov_b32_e32 v3, v1
	v_mov_b32_e32 v4, v1
	v_mov_b32_e32 v5, v1
	v_mov_b32_e32 v6, v1
	v_mov_b32_e32 v7, v1
	v_mov_b32_e32 v8, v1
	v_mov_b32_e32 v9, v1
	v_mov_b32_e32 v10, v1
	v_mov_b32_e32 v11, v1
	v_mov_b32_e32 v12, v1
	v_mov_b32_e32 v13, v1
	v_mov_b64_e32 v[78:79], v[14:15]
	v_mov_b64_e32 v[62:63], v[14:15]
	v_mov_b64_e32 v[46:47], v[14:15]
	v_mov_b64_e32 v[30:31], v[14:15]
	s_mov_b32 s0, 0
	s_mov_b32 s4, 0x8000
	s_movk_i32 s70, 0x4000
	s_movk_i32 s74, 0x2000
	v_mov_b32_e32 v241, 0
	s_mov_b32 s5, 6
	v_mov_b64_e32 v[76:77], v[12:13]
	v_mov_b64_e32 v[74:75], v[10:11]
	v_mov_b64_e32 v[72:73], v[8:9]
	v_mov_b64_e32 v[70:71], v[6:7]
	v_mov_b64_e32 v[68:69], v[4:5]
	v_mov_b64_e32 v[66:67], v[2:3]
	v_mov_b64_e32 v[64:65], v[0:1]
	v_mov_b64_e32 v[60:61], v[12:13]
	v_mov_b64_e32 v[58:59], v[10:11]
	v_mov_b64_e32 v[56:57], v[8:9]
	v_mov_b64_e32 v[54:55], v[6:7]
	v_mov_b64_e32 v[52:53], v[4:5]
	v_mov_b64_e32 v[50:51], v[2:3]
	v_mov_b64_e32 v[48:49], v[0:1]
	v_mov_b64_e32 v[44:45], v[12:13]
	v_mov_b64_e32 v[42:43], v[10:11]
	v_mov_b64_e32 v[40:41], v[8:9]
	v_mov_b64_e32 v[38:39], v[6:7]
	v_mov_b64_e32 v[36:37], v[4:5]
	v_mov_b64_e32 v[34:35], v[2:3]
	v_mov_b64_e32 v[32:33], v[0:1]
	v_mov_b64_e32 v[28:29], v[12:13]
	v_mov_b64_e32 v[26:27], v[10:11]
	v_mov_b64_e32 v[24:25], v[8:9]
	v_mov_b64_e32 v[22:23], v[6:7]
	v_mov_b64_e32 v[20:21], v[4:5]
	v_mov_b64_e32 v[18:19], v[2:3]
	v_mov_b64_e32 v[16:17], v[0:1]
	s_movk_i32 s40, 0x4000
	v_sub_f32_e32 v144, 0, v239
	v_sub_f32_e32 v145, 0, v239
	v_sub_f32_e32 v146, 0, v239
	v_sub_f32_e32 v147, 0, v239
	v_sub_f32_e32 v148, 0, v239
	v_sub_f32_e32 v149, 0, v239
	v_sub_f32_e32 v150, 0, v239
	v_sub_f32_e32 v151, 0, v239
	v_sub_f32_e32 v152, 0, v239
	v_sub_f32_e32 v153, 0, v239
	v_sub_f32_e32 v154, 0, v239
	v_sub_f32_e32 v155, 0, v239
	v_sub_f32_e32 v156, 0, v239
	v_sub_f32_e32 v157, 0, v239
	v_sub_f32_e32 v158, 0, v239
	v_sub_f32_e32 v159, 0, v239
.LBB0_411:
	v_add_u32_e32 v14, s0, v234
	v_add_u32_e32 v0, s74, v233
	ds_read_b64_tr_b16 v[214:215], v14 offset:33280
	ds_read_b128 v[216:219], v0 offset:4096
	ds_read_b64_tr_b16 v[212:213], v14 offset:32768
	ds_read_b128 v[10:13], v240 offset:1024
	s_waitcnt lgkmcnt(4)
	v_mfma_f32_32x32x16_bf16 v[128:143], v[204:207], v[208:211], v[144:159]
	v_add_f32_e32 v2, v96, v97
	v_add_f32_e32 v2, v98, v2
	v_add_f32_e32 v2, v99, v2
	v_add_f32_e32 v2, v100, v2
	v_add_f32_e32 v2, v101, v2
	v_cvt_pk_bf16_f32 v188, v96, v97
	v_cvt_pk_bf16_f32 v189, v98, v99
	ds_read_b64_tr_b16 v[204:205], v14 offset:36864
	ds_read_b64_tr_b16 v[206:207], v14 offset:37376
	ds_read_b128 v[226:229], v0 offset:4608
	v_mfma_f32_32x32x16_bf16 v[112:127], v[196:199], v[208:211], v[144:159]
	v_add_f32_e32 v2, v102, v2
	v_add_f32_e32 v2, v103, v2
	v_add_f32_e32 v2, v104, v2
	v_add_f32_e32 v6, v105, v2
	v_cvt_pk_bf16_f32 v190, v100, v101
	v_cvt_pk_bf16_f32 v191, v102, v103
	ds_read_b64_tr_b16 v[4:5], v14 offset:34304
	ds_read_b128 v[100:103], v0 offset:6144
	ds_read_b64_tr_b16 v[2:3], v14 offset:33792
	ds_read_b128 v[196:199], v240 offset:2048
	s_waitcnt lgkmcnt(7)
	v_mfma_f32_32x32x16_bf16 v[128:143], v[200:203], v[10:13], v[128:143]
	v_add_f32_e32 v6, v106, v6
	v_add_f32_e32 v6, v107, v6
	v_add_f32_e32 v6, v108, v6
	v_add_f32_e32 v15, v109, v6
	v_cvt_pk_bf16_f32 v184, v104, v105
	v_cvt_pk_bf16_f32 v185, v106, v107
	ds_read_b64_tr_b16 v[6:7], v14 offset:37888
	ds_read_b64_tr_b16 v[8:9], v14 offset:38400
	ds_read_b128 v[104:107], v0 offset:6656
	v_mfma_f32_32x32x16_bf16 v[112:127], v[192:195], v[10:13], v[112:127]
	v_add_f32_e32 v0, v110, v15
	v_add_f32_e32 v0, v111, v0
	v_add_f32_e32 v0, v80, v0
	v_add_f32_e32 v0, v81, v0
	v_cvt_pk_bf16_f32 v186, v108, v109
	v_cvt_pk_bf16_f32 v187, v110, v111
	ds_read_b64_tr_b16 v[12:13], v14 offset:35328
	ds_read_b64_tr_b16 v[10:11], v14 offset:34816
	ds_read_b128 v[108:111], v240 offset:3072
	s_waitcnt lgkmcnt(6)
	v_mfma_f32_32x32x16_bf16 v[128:143], v[216:219], v[196:199], v[128:143]
	v_add_f32_e32 v0, v82, v0
	v_add_f32_e32 v0, v83, v0
	v_add_f32_e32 v0, v84, v0
	v_add_f32_e32 v0, v85, v0
	v_cvt_pk_bf16_f32 v180, v80, v81
	v_cvt_pk_bf16_f32 v181, v82, v83
	ds_read_b64_tr_b16 v[96:97], v14 offset:38912
	ds_read_b64_tr_b16 v[98:99], v14 offset:39424
	v_mfma_f32_32x32x16_bf16 v[112:127], v[226:229], v[196:199], v[112:127]
	v_add_f32_e32 v0, v86, v0
	v_add_f32_e32 v0, v87, v0
	v_add_f32_e32 v0, v88, v0
	v_add_f32_e32 v0, v89, v0
	v_cvt_pk_bf16_f32 v182, v84, v85
	v_cvt_pk_bf16_f32 v183, v86, v87
	ds_read_b64_tr_b16 v[84:85], v14 offset:35840
	ds_read_b64_tr_b16 v[86:87], v14 offset:36352
	s_waitcnt lgkmcnt(4)
	v_mfma_f32_32x32x16_bf16 v[128:143], v[100:103], v[108:111], v[128:143]
	v_add_f32_e32 v0, v90, v0
	v_add_f32_e32 v0, v91, v0
	v_add_f32_e32 v0, v92, v0
	v_add_f32_e32 v0, v93, v0
	v_cvt_pk_bf16_f32 v176, v88, v89
	v_cvt_pk_bf16_f32 v177, v90, v91
	ds_read_b64_tr_b16 v[80:81], v14 offset:39936
	ds_read_b64_tr_b16 v[82:83], v14 offset:40448
	v_mfma_f32_32x32x16_bf16 v[112:127], v[104:107], v[108:111], v[112:127]
	v_add_f32_e32 v0, v94, v0
	v_add_f32_e32 v0, v95, v0
	v_add_f32_e32 v0, 0, v0
	v_cvt_pk_bf16_f32 v178, v92, v93
	v_cvt_pk_bf16_f32 v179, v94, v95
	v_max_f32_e32 v15, v129, v129
	v_max_f32_e32 v88, v128, v128
	v_max_f32_e32 v15, v88, v15
	s_nop 3
	v_max3_f32 v88, v130, v131, v113
	v_max3_f32 v15, v15, v112, v114
	v_max3_f32 v15, v15, v115, v132
	v_max3_f32 v88, v88, v134, v135
	v_max3_f32 v15, v15, v133, v116
	v_max3_f32 v88, v88, v118, v119
	v_max3_f32 v15, v15, v117, v136
	v_max3_f32 v88, v88, v138, v139
	v_max3_f32 v15, v15, v137, v120
	v_max3_f32 v88, v88, v122, v123
	v_max3_f32 v15, v15, v121, v140
	v_max3_f32 v88, v88, v142, v143
	v_max3_f32 v15, v15, v141, v124
	v_max3_f32 v88, v88, v126, v127
	v_max3_f32 v15, v15, v125, v88
	s_add_i32 s0, s74, 0xffffe000
	v_mov_b32_e32 v88, v15
	s_cmp_lg_u32 s74, 0
	s_nop 0
	v_permlane32_swap_b32_e32 v15, v88
	s_cselect_b32 s0, s0, 0x6000
	v_max_f32_e32 v88, v88, v88
	v_max_f32_e32 v15, v15, v15
	s_add_i32 s0, s0, s46
	s_mov_b32 s1, m0
	s_mov_b32 m0, s0
	s_nop 3
	global_load_lds_dwordx4 v236, s[24:25]
	s_mov_b32 m0, s1
	v_max_f32_e32 v15, v15, v88
	s_add_i32 s0, s4, s47
	s_mov_b32 s1, m0
	s_mov_b32 m0, s0
	s_nop 3
	global_load_lds_dwordx4 v237, s[14:15]
	s_mov_b32 m0, s1
	s_addk_i32 s0, 0x2000
	s_mov_b32 s1, m0
	s_mov_b32 m0, s0
	s_nop 3
	global_load_lds_dwordx4 v238, s[14:15]
	s_mov_b32 m0, s1
	v_cmp_lt_f32_e32 vcc, s87, v15
	s_cmp_lg_u64 vcc, 0
	v_add_f32_e32 v0, v241, v0
	s_cselect_b64 s[0:1], -1, 0
	s_cbranch_vccnz .LBB0_419
.LBB0_412:
	v_mfma_f32_32x32x16_bf16 v[64:79], v[188:191], v[212:215], v[64:79]
	v_exp_f32_e32 v128, v128
	v_exp_f32_e32 v129, v129
	ds_read_b64_tr_b16 v[88:89], v14 offset:40960
	ds_read_b64_tr_b16 v[90:91], v14 offset:41472
	v_mfma_f32_32x32x16_bf16 v[48:63], v[188:191], v[204:207], v[48:63]
	v_exp_f32_e32 v130, v130
	v_exp_f32_e32 v131, v131
	ds_read_b64_tr_b16 v[92:93], v14 offset:45056
	ds_read_b64_tr_b16 v[94:95], v14 offset:45568
	v_mfma_f32_32x32x16_bf16 v[64:79], v[184:187], v[2:5], v[64:79]
	v_exp_f32_e32 v132, v132
	v_exp_f32_e32 v133, v133
	ds_read_b64_tr_b16 v[2:3], v14 offset:41984
	ds_read_b64_tr_b16 v[4:5], v14 offset:42496
	v_mfma_f32_32x32x16_bf16 v[48:63], v[184:187], v[6:9], v[48:63]
	v_exp_f32_e32 v134, v134
	v_exp_f32_e32 v135, v135
	ds_read_b64_tr_b16 v[6:7], v14 offset:46080
	ds_read_b64_tr_b16 v[8:9], v14 offset:46592
	v_mfma_f32_32x32x16_bf16 v[64:79], v[180:183], v[10:13], v[64:79]
	v_exp_f32_e32 v136, v136
	v_exp_f32_e32 v137, v137
	ds_read_b64_tr_b16 v[10:11], v14 offset:43008
	ds_read_b64_tr_b16 v[12:13], v14 offset:43520
	s_waitcnt lgkmcnt(14)
	v_mfma_f32_32x32x16_bf16 v[48:63], v[180:183], v[96:99], v[48:63]
	v_exp_f32_e32 v138, v138
	v_exp_f32_e32 v139, v139
	ds_read_b64_tr_b16 v[96:97], v14 offset:47104
	ds_read_b64_tr_b16 v[98:99], v14 offset:47616
	s_waitcnt lgkmcnt(14)
	v_mfma_f32_32x32x16_bf16 v[64:79], v[176:179], v[84:87], v[64:79]
	v_exp_f32_e32 v140, v140
	v_exp_f32_e32 v141, v141
	ds_read_b64_tr_b16 v[84:85], v14 offset:44032
	ds_read_b64_tr_b16 v[86:87], v14 offset:44544
	s_waitcnt lgkmcnt(14)
	v_mfma_f32_32x32x16_bf16 v[48:63], v[176:179], v[80:83], v[48:63]
	v_exp_f32_e32 v142, v142
	v_exp_f32_e32 v143, v143
	ds_read_b64_tr_b16 v[100:101], v14 offset:48128
	ds_read_b64_tr_b16 v[102:103], v14 offset:48640
	s_waitcnt lgkmcnt(14)
	v_mfma_f32_32x32x16_bf16 v[32:47], v[188:191], v[88:91], v[32:47]
	v_exp_f32_e32 v112, v112
	v_exp_f32_e32 v113, v113
	s_waitcnt lgkmcnt(12)
	v_mfma_f32_32x32x16_bf16 v[16:31], v[188:191], v[92:95], v[16:31]
	v_exp_f32_e32 v114, v114
	v_exp_f32_e32 v115, v115
	s_waitcnt lgkmcnt(10)
	v_mfma_f32_32x32x16_bf16 v[32:47], v[184:187], v[2:5], v[32:47]
	v_exp_f32_e32 v116, v116
	v_exp_f32_e32 v117, v117
	s_waitcnt lgkmcnt(8)
	v_mfma_f32_32x32x16_bf16 v[16:31], v[184:187], v[6:9], v[16:31]
	v_exp_f32_e32 v118, v118
	v_exp_f32_e32 v119, v119
	v_add_u32_e32 v15, s70, v233
	ds_read_b128 v[2:5], v15
	s_waitcnt lgkmcnt(7)
	v_mfma_f32_32x32x16_bf16 v[32:47], v[180:183], v[10:13], v[32:47]
	v_exp_f32_e32 v120, v120
	v_exp_f32_e32 v121, v121
	ds_read_b128 v[6:9], v15 offset:512
	s_waitcnt lgkmcnt(6)
	v_mfma_f32_32x32x16_bf16 v[16:31], v[180:183], v[96:99], v[16:31]
	v_exp_f32_e32 v122, v122
	v_exp_f32_e32 v123, v123
	ds_read_b128 v[192:195], v15 offset:2048
	s_waitcnt lgkmcnt(5)
	v_mfma_f32_32x32x16_bf16 v[32:47], v[176:179], v[84:87], v[32:47]
	v_exp_f32_e32 v124, v124
	v_exp_f32_e32 v125, v125
	ds_read_b128 v[10:13], v15 offset:2560
	ds_read_b128 v[80:83], v240
	s_waitcnt lgkmcnt(5)
	v_mfma_f32_32x32x16_bf16 v[16:31], v[176:179], v[100:103], v[16:31]
	v_exp_f32_e32 v126, v126
	v_exp_f32_e32 v127, v127
	s_waitcnt vmcnt(3) lgkmcnt(0)
	s_barrier
	s_andn2_b64 vcc, exec, s[0:1]
	s_cbranch_vccnz .LBB0_414
	s_waitcnt lgkmcnt(0)
	s_mov_b32 s0, 0
	s_nop 0
	v_mbcnt_lo_u32_b32 v14, -1, s0
	v_mbcnt_hi_u32_b32 v14, -1, v14
	v_ashrrev_i32_e32 v14, 3, v14
	v_lshlrev_b32_e32 v14, 2, v14
	v_and_b32_e32 v14, -16, v14
	v_add_u32_e32 v14, s51, v14
	ds_read_b128 v[84:87], v14 offset:96
	ds_read_b128 v[88:91], v14 offset:64
	ds_read_b128 v[92:95], v14 offset:32
	ds_read_b128 v[96:99], v14
	s_waitcnt lgkmcnt(3)
	v_pk_mul_f32 v[76:77], v[76:77], v[84:85]
	s_waitcnt lgkmcnt(2)
	v_pk_mul_f32 v[72:73], v[72:73], v[88:89]
	s_waitcnt lgkmcnt(1)
	v_pk_mul_f32 v[68:69], v[68:69], v[92:93]
	v_pk_mul_f32 v[78:79], v[78:79], v[86:87]
	v_pk_mul_f32 v[74:75], v[74:75], v[90:91]
	v_pk_mul_f32 v[70:71], v[70:71], v[94:95]
	s_waitcnt lgkmcnt(0)
	v_pk_mul_f32 v[66:67], v[66:67], v[98:99]
	v_pk_mul_f32 v[64:65], v[64:65], v[96:97]
	v_pk_mul_f32 v[60:61], v[60:61], v[84:85]
	v_pk_mul_f32 v[56:57], v[56:57], v[88:89]
	v_pk_mul_f32 v[52:53], v[52:53], v[92:93]
	v_pk_mul_f32 v[62:63], v[62:63], v[86:87]
	v_pk_mul_f32 v[58:59], v[58:59], v[90:91]
	v_pk_mul_f32 v[54:55], v[54:55], v[94:95]
	v_pk_mul_f32 v[50:51], v[50:51], v[98:99]
	v_pk_mul_f32 v[48:49], v[48:49], v[96:97]
	v_pk_mul_f32 v[44:45], v[44:45], v[84:85]
	v_pk_mul_f32 v[40:41], v[40:41], v[88:89]
	v_pk_mul_f32 v[36:37], v[36:37], v[92:93]
	v_pk_mul_f32 v[46:47], v[46:47], v[86:87]
	v_pk_mul_f32 v[42:43], v[42:43], v[90:91]
	v_pk_mul_f32 v[38:39], v[38:39], v[94:95]
	v_pk_mul_f32 v[34:35], v[34:35], v[98:99]
	v_pk_mul_f32 v[32:33], v[32:33], v[96:97]
	v_pk_mul_f32 v[28:29], v[28:29], v[84:85]
	v_pk_mul_f32 v[24:25], v[24:25], v[88:89]
	v_pk_mul_f32 v[20:21], v[20:21], v[92:93]
	v_pk_mul_f32 v[30:31], v[30:31], v[86:87]
	v_pk_mul_f32 v[26:27], v[26:27], v[90:91]
	v_pk_mul_f32 v[22:23], v[22:23], v[94:95]
	v_pk_mul_f32 v[18:19], v[18:19], v[98:99]
	v_pk_mul_f32 v[16:17], v[16:17], v[96:97]
.LBB0_414:
	s_add_u32 s2, s24, 0x10000
	s_addc_u32 s3, s25, 0
	s_add_u32 s0, s14, 0x10000
	s_addc_u32 s1, s15, 0
	s_add_i32 s41, s4, 0x4000
	s_cmpk_lg_u32 s4, 0x8000
	s_cselect_b32 s69, s41, 0
	v_add_u32_e32 v14, s40, v234
	ds_read_b64_tr_b16 v[200:201], v14 offset:32768
	ds_read_b64_tr_b16 v[202:203], v14 offset:33280
	ds_read_b128 v[204:207], v15 offset:4096
	ds_read_b128 v[208:211], v240 offset:1024
	s_waitcnt lgkmcnt(4)
	v_mfma_f32_32x32x16_bf16 v[96:111], v[2:5], v[80:83], v[144:159]
	v_add_f32_e32 v84, v128, v129
	v_add_f32_e32 v84, v130, v84
	v_add_f32_e32 v84, v131, v84
	v_add_f32_e32 v84, v132, v84
	v_add_f32_e32 v84, v133, v84
	v_cvt_pk_bf16_f32 v188, v128, v129
	v_cvt_pk_bf16_f32 v189, v130, v131
	ds_read_b64_tr_b16 v[198:199], v14 offset:37376
	ds_read_b64_tr_b16 v[196:197], v14 offset:36864
	ds_read_b128 v[212:215], v15 offset:4608
	v_add_f32_e32 v2, v134, v84
	v_mfma_f32_32x32x16_bf16 v[80:95], v[6:9], v[80:83], v[144:159]
	v_add_f32_e32 v2, v135, v2
	v_add_f32_e32 v2, v136, v2
	v_add_f32_e32 v128, v137, v2
	v_cvt_pk_bf16_f32 v190, v132, v133
	v_cvt_pk_bf16_f32 v191, v134, v135
	ds_read_b64_tr_b16 v[2:3], v14 offset:33792
	ds_read_b64_tr_b16 v[4:5], v14 offset:34304
	ds_read_b128 v[132:135], v15 offset:6144
	ds_read_b128 v[216:219], v240 offset:2048
	s_waitcnt lgkmcnt(7)
	v_mfma_f32_32x32x16_bf16 v[96:111], v[192:195], v[208:211], v[96:111]
	v_add_f32_e32 v6, v138, v128
	v_add_f32_e32 v6, v139, v6
	v_add_f32_e32 v6, v140, v6
	v_add_f32_e32 v128, v141, v6
	v_cvt_pk_bf16_f32 v184, v136, v137
	v_cvt_pk_bf16_f32 v185, v138, v139
	ds_read_b64_tr_b16 v[8:9], v14 offset:38400
	ds_read_b64_tr_b16 v[6:7], v14 offset:37888
	ds_read_b128 v[136:139], v15 offset:6656
	v_mfma_f32_32x32x16_bf16 v[80:95], v[10:13], v[208:211], v[80:95]
	v_add_f32_e32 v10, v142, v128
	v_add_f32_e32 v10, v143, v10
	v_add_f32_e32 v10, v112, v10
	v_add_f32_e32 v15, v113, v10
	v_cvt_pk_bf16_f32 v186, v140, v141
	v_cvt_pk_bf16_f32 v187, v142, v143
	ds_read_b64_tr_b16 v[12:13], v14 offset:35328
	ds_read_b64_tr_b16 v[10:11], v14 offset:34816
	ds_read_b128 v[140:143], v240 offset:3072
	s_waitcnt lgkmcnt(6)
	v_mfma_f32_32x32x16_bf16 v[96:111], v[204:207], v[216:219], v[96:111]
	v_add_f32_e32 v15, v114, v15
	v_add_f32_e32 v15, v115, v15
	v_add_f32_e32 v15, v116, v15
	v_add_f32_e32 v15, v117, v15
	v_cvt_pk_bf16_f32 v180, v112, v113
	v_cvt_pk_bf16_f32 v181, v114, v115
	ds_read_b64_tr_b16 v[128:129], v14 offset:38912
	ds_read_b64_tr_b16 v[130:131], v14 offset:39424
	v_mfma_f32_32x32x16_bf16 v[80:95], v[212:215], v[216:219], v[80:95]
	v_add_f32_e32 v15, v118, v15
	v_add_f32_e32 v15, v119, v15
	v_add_f32_e32 v15, v120, v15
	v_add_f32_e32 v15, v121, v15
	v_cvt_pk_bf16_f32 v182, v116, v117
	v_cvt_pk_bf16_f32 v183, v118, v119
	ds_read_b64_tr_b16 v[116:117], v14 offset:35840
	ds_read_b64_tr_b16 v[118:119], v14 offset:36352
	s_waitcnt lgkmcnt(4)
	v_mfma_f32_32x32x16_bf16 v[96:111], v[132:135], v[140:143], v[96:111]
	v_add_f32_e32 v15, v122, v15
	v_add_f32_e32 v15, v123, v15
	v_add_f32_e32 v15, v124, v15
	v_add_f32_e32 v15, v125, v15
	v_cvt_pk_bf16_f32 v176, v120, v121
	v_cvt_pk_bf16_f32 v177, v122, v123
	ds_read_b64_tr_b16 v[112:113], v14 offset:39936
	ds_read_b64_tr_b16 v[114:115], v14 offset:40448
	v_mfma_f32_32x32x16_bf16 v[80:95], v[136:139], v[140:143], v[80:95]
	v_add_f32_e32 v15, v126, v15
	v_add_f32_e32 v15, v127, v15
	v_add_f32_e32 v15, 0, v15
	v_cvt_pk_bf16_f32 v178, v124, v125
	v_cvt_pk_bf16_f32 v179, v126, v127
	s_nop 0
	v_add_f32_e32 v241, v0, v15
	v_max_f32_e32 v0, v97, v97
	v_max_f32_e32 v15, v96, v96
	v_max_f32_e32 v0, v15, v0
	s_nop 1
	v_max3_f32 v15, v98, v99, v81
	v_max3_f32 v0, v0, v80, v82
	v_max3_f32 v0, v0, v83, v100
	v_max3_f32 v15, v15, v102, v103
	v_max3_f32 v0, v0, v101, v84
	v_max3_f32 v15, v15, v86, v87
	v_max3_f32 v0, v0, v85, v104
	v_max3_f32 v15, v15, v106, v107
	v_max3_f32 v0, v0, v105, v88
	v_max3_f32 v15, v15, v90, v91
	v_max3_f32 v0, v0, v89, v108
	v_max3_f32 v15, v15, v110, v111
	v_max3_f32 v0, v0, v109, v92
	v_max3_f32 v15, v15, v94, v95
	v_max3_f32 v0, v0, v93, v15
	s_add_i32 s40, s70, 0xffffe000
	v_mov_b32_e32 v15, v0
	s_cmp_lg_u32 s70, 0
	s_nop 0
	v_permlane32_swap_b32_e32 v0, v15
	s_cselect_b32 s40, s40, 0x6000
	v_max_f32_e32 v15, v15, v15
	v_max_f32_e32 v0, v0, v0
	s_add_i32 s40, s40, s46
	s_mov_b32 s41, m0
	s_mov_b32 m0, s40
	s_nop 3
	global_load_lds_dwordx4 v236, s[2:3]
	s_mov_b32 m0, s41
	v_max_f32_e32 v0, v0, v15
	s_add_i32 s2, s69, s47
	s_mov_b32 s3, m0
	s_mov_b32 m0, s2
	s_nop 3
	global_load_lds_dwordx4 v237, s[0:1]
	s_mov_b32 m0, s3
	s_addk_i32 s2, 0x2000
	s_mov_b32 s3, m0
	s_mov_b32 m0, s2
	s_nop 3
	global_load_lds_dwordx4 v238, s[0:1]
	s_mov_b32 m0, s3
	v_cmp_lt_f32_e32 vcc, s87, v0
	s_cmp_lg_u64 vcc, 0
	s_cselect_b64 s[0:1], -1, 0
	s_cbranch_vccnz .LBB0_422
.LBB0_415:
	s_add_i32 s2, s70, 0x2000
	s_cmpk_lg_i32 s70, 0x6000
	s_cselect_b32 s74, s2, 0
	v_mfma_f32_32x32x16_bf16 v[64:79], v[188:191], v[200:203], v[64:79]
	v_exp_f32_e32 v96, v96
	v_exp_f32_e32 v97, v97
	ds_read_b64_tr_b16 v[120:121], v14 offset:40960
	ds_read_b64_tr_b16 v[122:123], v14 offset:41472
	v_mfma_f32_32x32x16_bf16 v[48:63], v[188:191], v[196:199], v[48:63]
	v_exp_f32_e32 v98, v98
	v_exp_f32_e32 v99, v99
	ds_read_b64_tr_b16 v[124:125], v14 offset:45056
	ds_read_b64_tr_b16 v[126:127], v14 offset:45568
	v_mfma_f32_32x32x16_bf16 v[64:79], v[184:187], v[2:5], v[64:79]
	v_exp_f32_e32 v100, v100
	v_exp_f32_e32 v101, v101
	ds_read_b64_tr_b16 v[2:3], v14 offset:41984
	ds_read_b64_tr_b16 v[4:5], v14 offset:42496
	v_mfma_f32_32x32x16_bf16 v[48:63], v[184:187], v[6:9], v[48:63]
	v_exp_f32_e32 v102, v102
	v_exp_f32_e32 v103, v103
	ds_read_b64_tr_b16 v[6:7], v14 offset:46080
	ds_read_b64_tr_b16 v[8:9], v14 offset:46592
	v_mfma_f32_32x32x16_bf16 v[64:79], v[180:183], v[10:13], v[64:79]
	v_exp_f32_e32 v104, v104
	v_exp_f32_e32 v105, v105
	ds_read_b64_tr_b16 v[10:11], v14 offset:43008
	ds_read_b64_tr_b16 v[12:13], v14 offset:43520
	s_waitcnt lgkmcnt(14)
	v_mfma_f32_32x32x16_bf16 v[48:63], v[180:183], v[128:131], v[48:63]
	v_exp_f32_e32 v106, v106
	v_exp_f32_e32 v107, v107
	ds_read_b64_tr_b16 v[128:129], v14 offset:47104
	ds_read_b64_tr_b16 v[130:131], v14 offset:47616
	s_waitcnt lgkmcnt(14)
	v_mfma_f32_32x32x16_bf16 v[64:79], v[176:179], v[116:119], v[64:79]
	v_exp_f32_e32 v108, v108
	v_exp_f32_e32 v109, v109
	ds_read_b64_tr_b16 v[116:117], v14 offset:44032
	ds_read_b64_tr_b16 v[118:119], v14 offset:44544
	s_waitcnt lgkmcnt(14)
	v_mfma_f32_32x32x16_bf16 v[48:63], v[176:179], v[112:115], v[48:63]
	v_exp_f32_e32 v110, v110
	v_exp_f32_e32 v111, v111
	ds_read_b64_tr_b16 v[112:113], v14 offset:48128
	ds_read_b64_tr_b16 v[114:115], v14 offset:48640
	s_waitcnt lgkmcnt(14)
	v_mfma_f32_32x32x16_bf16 v[32:47], v[188:191], v[120:123], v[32:47]
	v_exp_f32_e32 v80, v80
	v_exp_f32_e32 v81, v81
	s_waitcnt lgkmcnt(12)
	v_mfma_f32_32x32x16_bf16 v[16:31], v[188:191], v[124:127], v[16:31]
	v_exp_f32_e32 v82, v82
	v_exp_f32_e32 v83, v83
	s_waitcnt lgkmcnt(10)
	v_mfma_f32_32x32x16_bf16 v[32:47], v[184:187], v[2:5], v[32:47]
	v_exp_f32_e32 v84, v84
	v_exp_f32_e32 v85, v85
	s_waitcnt lgkmcnt(8)
	v_mfma_f32_32x32x16_bf16 v[16:31], v[184:187], v[6:9], v[16:31]
	v_exp_f32_e32 v86, v86
	v_exp_f32_e32 v87, v87
	v_add_u32_e32 v0, s74, v233
	ds_read_b128 v[204:207], v0
	s_waitcnt lgkmcnt(7)
	v_mfma_f32_32x32x16_bf16 v[32:47], v[180:183], v[10:13], v[32:47]
	v_exp_f32_e32 v88, v88
	v_exp_f32_e32 v89, v89
	ds_read_b128 v[196:199], v0 offset:512
	s_waitcnt lgkmcnt(6)
	v_mfma_f32_32x32x16_bf16 v[16:31], v[180:183], v[128:131], v[16:31]
	v_exp_f32_e32 v90, v90
	v_exp_f32_e32 v91, v91
	ds_read_b128 v[200:203], v0 offset:2048
	s_waitcnt lgkmcnt(5)
	v_mfma_f32_32x32x16_bf16 v[32:47], v[176:179], v[116:119], v[32:47]
	v_exp_f32_e32 v92, v92
	v_exp_f32_e32 v93, v93
	ds_read_b128 v[192:195], v0 offset:2560
	ds_read_b128 v[208:211], v240
	s_waitcnt lgkmcnt(5)
	v_mfma_f32_32x32x16_bf16 v[16:31], v[176:179], v[112:115], v[16:31]
	v_exp_f32_e32 v94, v94
	v_exp_f32_e32 v95, v95
	s_waitcnt vmcnt(3) lgkmcnt(0)
	s_barrier
	s_andn2_b64 vcc, exec, s[0:1]
	s_cbranch_vccnz .LBB0_417
	s_waitcnt lgkmcnt(0)
	s_mov_b32 s0, 0
	s_nop 0
	v_mbcnt_lo_u32_b32 v0, -1, s0
	v_mbcnt_hi_u32_b32 v0, -1, v0
	v_ashrrev_i32_e32 v0, 3, v0
	v_lshlrev_b32_e32 v0, 2, v0
	v_and_b32_e32 v0, -16, v0
	v_add_u32_e32 v0, s51, v0
	ds_read_b128 v[2:5], v0 offset:96
	ds_read_b128 v[6:9], v0 offset:64
	ds_read_b128 v[10:13], v0 offset:32
	ds_read_b128 v[112:115], v0
	s_waitcnt lgkmcnt(3)
	v_pk_mul_f32 v[76:77], v[76:77], v[2:3]
	s_waitcnt lgkmcnt(2)
	v_pk_mul_f32 v[72:73], v[72:73], v[6:7]
	s_waitcnt lgkmcnt(1)
	v_pk_mul_f32 v[68:69], v[68:69], v[10:11]
	v_pk_mul_f32 v[78:79], v[78:79], v[4:5]
	v_pk_mul_f32 v[74:75], v[74:75], v[8:9]
	v_pk_mul_f32 v[70:71], v[70:71], v[12:13]
	s_waitcnt lgkmcnt(0)
	v_pk_mul_f32 v[66:67], v[66:67], v[114:115]
	v_pk_mul_f32 v[64:65], v[64:65], v[112:113]
	v_pk_mul_f32 v[60:61], v[60:61], v[2:3]
	v_pk_mul_f32 v[56:57], v[56:57], v[6:7]
	v_pk_mul_f32 v[52:53], v[52:53], v[10:11]
	v_pk_mul_f32 v[62:63], v[62:63], v[4:5]
	v_pk_mul_f32 v[58:59], v[58:59], v[8:9]
	v_pk_mul_f32 v[54:55], v[54:55], v[12:13]
	v_pk_mul_f32 v[50:51], v[50:51], v[114:115]
	v_pk_mul_f32 v[48:49], v[48:49], v[112:113]
	v_pk_mul_f32 v[44:45], v[44:45], v[2:3]
	v_pk_mul_f32 v[40:41], v[40:41], v[6:7]
	v_pk_mul_f32 v[36:37], v[36:37], v[10:11]
	v_pk_mul_f32 v[46:47], v[46:47], v[4:5]
	v_pk_mul_f32 v[42:43], v[42:43], v[8:9]
	v_pk_mul_f32 v[38:39], v[38:39], v[12:13]
	v_pk_mul_f32 v[34:35], v[34:35], v[114:115]
	v_pk_mul_f32 v[32:33], v[32:33], v[112:113]
	v_pk_mul_f32 v[28:29], v[28:29], v[2:3]
	v_pk_mul_f32 v[24:25], v[24:25], v[6:7]
	v_pk_mul_f32 v[20:21], v[20:21], v[10:11]
	v_pk_mul_f32 v[30:31], v[30:31], v[4:5]
	v_pk_mul_f32 v[26:27], v[26:27], v[8:9]
	v_pk_mul_f32 v[22:23], v[22:23], v[12:13]
	v_pk_mul_f32 v[18:19], v[18:19], v[114:115]
	v_pk_mul_f32 v[16:17], v[16:17], v[112:113]

.LBB0_419:
	v_max_f32_e32 v15, v15, v15
	v_max_f32_e32 v88, 0, v15
	v_exp_f32_e64 v15, -v88
	s_mov_b32 s2, 0
	s_nop 0
	v_mbcnt_lo_u32_b32 v89, -1, s2
	v_mbcnt_hi_u32_b32 v89, -1, v89
	v_cmp_gt_i32_e32 vcc, 32, v89
	s_and_saveexec_b64 s[2:3], vcc
	v_lshl_add_u32 v89, v89, 2, s51
	ds_write_b32 v89, v15
	s_or_b64 exec, exec, s[2:3]
	v_add_f32_e32 v239, v239, v88
	v_sub_f32_e32 v128, v128, v88
	v_sub_f32_e32 v129, v129, v88
	v_sub_f32_e32 v130, v130, v88
	v_sub_f32_e32 v131, v131, v88
	v_sub_f32_e32 v132, v132, v88
	v_sub_f32_e32 v133, v133, v88
	v_sub_f32_e32 v134, v134, v88
	v_sub_f32_e32 v135, v135, v88
	v_sub_f32_e32 v136, v136, v88
	v_sub_f32_e32 v137, v137, v88
	v_sub_f32_e32 v138, v138, v88
	v_sub_f32_e32 v139, v139, v88
	v_sub_f32_e32 v140, v140, v88
	v_sub_f32_e32 v141, v141, v88
	v_sub_f32_e32 v142, v142, v88
	v_sub_f32_e32 v143, v143, v88
	v_sub_f32_e32 v112, v112, v88
	v_sub_f32_e32 v113, v113, v88
	v_sub_f32_e32 v114, v114, v88
	v_sub_f32_e32 v115, v115, v88
	v_sub_f32_e32 v116, v116, v88
	v_sub_f32_e32 v117, v117, v88
	v_sub_f32_e32 v118, v118, v88
	v_sub_f32_e32 v119, v119, v88
	v_sub_f32_e32 v120, v120, v88
	v_sub_f32_e32 v121, v121, v88
	v_sub_f32_e32 v122, v122, v88
	v_sub_f32_e32 v123, v123, v88
	v_sub_f32_e32 v124, v124, v88
	v_sub_f32_e32 v125, v125, v88
	v_sub_f32_e32 v126, v126, v88
	v_sub_f32_e32 v127, v127, v88
	v_sub_f32_e32 v144, v144, v88
	v_sub_f32_e32 v145, v145, v88
	v_sub_f32_e32 v146, v146, v88
	v_sub_f32_e32 v147, v147, v88
	v_sub_f32_e32 v148, v148, v88
	v_sub_f32_e32 v149, v149, v88
	v_sub_f32_e32 v150, v150, v88
	v_sub_f32_e32 v151, v151, v88
	v_sub_f32_e32 v152, v152, v88
	v_sub_f32_e32 v153, v153, v88
	v_sub_f32_e32 v154, v154, v88
	v_sub_f32_e32 v155, v155, v88
	v_sub_f32_e32 v156, v156, v88
	v_sub_f32_e32 v157, v157, v88
	v_sub_f32_e32 v158, v158, v88
	v_sub_f32_e32 v159, v159, v88
	v_mul_f32_e32 v0, v0, v15
	s_branch .LBB0_412
.LBB0_422:
	v_max_f32_e32 v0, v0, v0
	v_max_f32_e32 v15, 0, v0
	v_exp_f32_e64 v0, -v15
	s_mov_b32 s2, 0
	s_nop 0
	v_mbcnt_lo_u32_b32 v120, -1, s2
	v_mbcnt_hi_u32_b32 v120, -1, v120
	v_cmp_gt_i32_e32 vcc, 32, v120
	s_and_saveexec_b64 s[2:3], vcc
	v_lshl_add_u32 v120, v120, 2, s51
	ds_write_b32 v120, v0
	s_or_b64 exec, exec, s[2:3]
	v_add_f32_e32 v239, v239, v15
	v_sub_f32_e32 v96, v96, v15
	v_sub_f32_e32 v97, v97, v15
	v_sub_f32_e32 v98, v98, v15
	v_sub_f32_e32 v99, v99, v15
	v_sub_f32_e32 v100, v100, v15
	v_sub_f32_e32 v101, v101, v15
	v_sub_f32_e32 v102, v102, v15
	v_sub_f32_e32 v103, v103, v15
	v_sub_f32_e32 v104, v104, v15
	v_sub_f32_e32 v105, v105, v15
	v_sub_f32_e32 v106, v106, v15
	v_sub_f32_e32 v107, v107, v15
	v_sub_f32_e32 v108, v108, v15
	v_sub_f32_e32 v109, v109, v15
	v_sub_f32_e32 v110, v110, v15
	v_sub_f32_e32 v111, v111, v15
	v_sub_f32_e32 v80, v80, v15
	v_sub_f32_e32 v81, v81, v15
	v_sub_f32_e32 v82, v82, v15
	v_sub_f32_e32 v83, v83, v15
	v_sub_f32_e32 v84, v84, v15
	v_sub_f32_e32 v85, v85, v15
	v_sub_f32_e32 v86, v86, v15
	v_sub_f32_e32 v87, v87, v15
	v_sub_f32_e32 v88, v88, v15
	v_sub_f32_e32 v89, v89, v15
	v_sub_f32_e32 v90, v90, v15
	v_sub_f32_e32 v91, v91, v15
	v_sub_f32_e32 v92, v92, v15
	v_sub_f32_e32 v93, v93, v15
	v_sub_f32_e32 v94, v94, v15
	v_sub_f32_e32 v95, v95, v15
	v_sub_f32_e32 v144, v144, v15
	v_sub_f32_e32 v145, v145, v15
	v_sub_f32_e32 v146, v146, v15
	v_sub_f32_e32 v147, v147, v15
	v_sub_f32_e32 v148, v148, v15
	v_sub_f32_e32 v149, v149, v15
	v_sub_f32_e32 v150, v150, v15
	v_sub_f32_e32 v151, v151, v15
	v_sub_f32_e32 v152, v152, v15
	v_sub_f32_e32 v153, v153, v15
	v_sub_f32_e32 v154, v154, v15
	v_sub_f32_e32 v155, v155, v15
	v_sub_f32_e32 v156, v156, v15
	v_sub_f32_e32 v157, v157, v15
	v_sub_f32_e32 v158, v158, v15
	v_sub_f32_e32 v159, v159, v15
	v_mul_f32_e32 v241, v241, v0
	s_branch .LBB0_415
